# HGRN c3: dir-0 pass also touches the item's GH (gate) tile used by the readout
# speedup vs baseline: 1.0016x; 1.0016x over previous
; DEV void phase_hg_c3(const Params& p, char* smem) {
;     ...
;       __syncthreads();
;       const int k = tid & 127, half = tid >> 7;
;       {
;         const bf16_t* lsrc = (dir ? LBp : LFp);
; #pragma unroll
;         for (int i = 0; i < 4; i++) {
;           int id = tid + i * 256; int s = id >> 4, cc = id & 15;
;           const size_t go = (size_t)(r0 + s) * 1024 + h * 128 + cc * 8;
;           uint4 u = *(const uint4*)(IH + go);
;           *(uint4*)(Kin + s * 144 + cc * 8) = *(const uint4*)(lsrc + go);
;           *(uint4*)(Qin + s * 144 + cc * 8) = *(const uint4*)(QH + go);
;           bf16_t* vt = Vt + (cc * 8) * 80 + s;
;           vt[0] = (bf16_t)(u.x & 0xffff); vt[80] = (bf16_t)(u.x >> 16); vt[160] = (bf16_t)(u.y & 0xffff); vt[240] = (bf16_t)(u.y >> 16);
;           vt[320] = (bf16_t)(u.z & 0xffff); vt[400] = (bf16_t)(u.z >> 16); vt[480] = (bf16_t)(u.w & 0xffff); vt[560] = (bf16_t)(u.w >> 16);
;         }
;       }
;       u32x4 spr[8];
;       {
;         const bf16_t* sp = DS + ((size_t)(bh * 2 + dir) * 132 + hg_step(cidx, dir)) * 16384;
; #pragma unroll
;         for (int i = 0; i < 8; i++) { int id = tid + i * 256; int row = id >> 4, cc = id & 15; spr[i] = *(const u32x4*)(sp + row * 128 + cc * 8); }
.LBB0_279:
	s_xor_b64 s[78:79], s[6:7], -1
	s_and_b64 s[14:15], s[6:7], exec
	s_mov_b32 s14, 0xe400000
	s_cselect_b32 s14, s14, 0x10500000
	s_add_u32 s14, s28, s14
	s_addc_u32 s15, s29, 0
	s_waitcnt vmcnt(19)
	v_lshl_add_u64 v[38:39], v[84:85], 1, s[14:15]
	v_lshl_add_u64 v[42:43], v[90:91], 1, s[14:15]
	v_lshl_add_u64 v[46:47], v[96:97], 1, s[14:15]
	v_lshl_add_u64 v[50:51], v[102:103], 1, s[14:15]
	v_lshl_add_u64 v[176:177], v[192:193], 0, v[244:245]
	v_lshl_add_u64 v[184:185], v[192:193], 1, v[244:245]
	v_lshl_add_u64 v[236:237], v[192:193], 0, v[184:185]
	s_waitcnt lgkmcnt(0)
	s_barrier
	global_load_dwordx4 v[38:41], v[38:39], off
	global_load_dwordx4 v[34:37], v[244:245], off
	global_load_dwordx4 v[172:175], v[88:89], off
	global_load_dwordx4 v[42:45], v[42:43], off
	global_load_dwordx4 v[176:179], v[176:177], off
	global_load_dwordx4 v[180:183], v[94:95], off
	global_load_dwordx4 v[46:49], v[46:47], off
	global_load_dwordx4 v[184:187], v[184:185], off
	global_load_dwordx4 v[188:191], v[100:101], off
	global_load_dwordx4 v[50:53], v[50:51], off
	global_load_dwordx4 v[236:239], v[236:237], off
	global_load_dwordx4 v[240:243], v[106:107], off
	s_waitcnt vmcnt(11)
	ds_write_b128 v133, v[38:41]
	s_waitcnt vmcnt(10)
	ds_write_b16 v194, v34 offset:36864
	ds_write_b16_d16_hi v194, v34 offset:37024
	ds_write_b16 v194, v35 offset:37184
	ds_write_b16_d16_hi v194, v35 offset:37344
	ds_write_b16 v194, v36 offset:37504
	ds_write_b16_d16_hi v194, v36 offset:37664
	ds_write_b16 v194, v37 offset:37824
	ds_write_b16_d16_hi v194, v37 offset:37984
	s_waitcnt vmcnt(9)
	ds_write_b128 v132, v[172:175]
	s_waitcnt vmcnt(8)
	ds_write_b128 v137, v[42:45]
	s_waitcnt vmcnt(7)
	ds_write_b16 v194, v176 offset:36896
	ds_write_b16_d16_hi v194, v176 offset:37056
	ds_write_b16 v194, v177 offset:37216
	ds_write_b16_d16_hi v194, v177 offset:37376
	ds_write_b16 v194, v178 offset:37536
	ds_write_b16_d16_hi v194, v178 offset:37696
	ds_write_b16 v194, v179 offset:37856
	ds_write_b16_d16_hi v194, v179 offset:38016
	s_waitcnt vmcnt(6)
	ds_write_b128 v136, v[180:183]
	s_waitcnt vmcnt(5)
	ds_write_b128 v141, v[46:49]
	s_waitcnt vmcnt(4)
	ds_write_b16 v194, v184 offset:36928
	ds_write_b16_d16_hi v194, v184 offset:37088
	ds_write_b16 v194, v185 offset:37248
	ds_write_b16_d16_hi v194, v185 offset:37408
	ds_write_b16 v194, v186 offset:37568
	ds_write_b16_d16_hi v194, v186 offset:37728
	ds_write_b16 v194, v187 offset:37888
	ds_write_b16_d16_hi v194, v187 offset:38048
	s_waitcnt vmcnt(3)
	ds_write_b128 v140, v[188:191]
	s_waitcnt vmcnt(2)
	ds_write_b128 v145, v[50:53]
	s_waitcnt vmcnt(1)
	ds_write_b16 v194, v236 offset:36960
	ds_write_b16_d16_hi v194, v236 offset:37120
	ds_write_b16 v194, v237 offset:37280
	ds_write_b16_d16_hi v194, v237 offset:37440
	ds_write_b16 v194, v238 offset:37600
	ds_write_b16_d16_hi v194, v238 offset:37760
	ds_write_b16 v194, v239 offset:37920
	ds_write_b16_d16_hi v194, v239 offset:38080
	s_waitcnt vmcnt(0)
	ds_write_b128 v144, v[240:243]
	s_cmp_lg_u64 s[6:7], 0
	s_cbranch_scc0 .Lc3_pf_dir1
	s_add_u32 s98, s14, 0x2100000
	s_addc_u32 s99, s15, 0
	v_lshl_add_u64 v[188:189], v[84:85], 1, s[98:99]
	global_load_dwordx4 v[184:187], v[188:189], off
	v_lshl_add_u64 v[188:189], v[90:91], 1, s[98:99]
	global_load_dwordx4 v[184:187], v[188:189], off
	v_lshl_add_u64 v[188:189], v[96:97], 1, s[98:99]
	global_load_dwordx4 v[184:187], v[188:189], off
	v_lshl_add_u64 v[188:189], v[102:103], 1, s[98:99]
	global_load_dwordx4 v[184:187], v[188:189], off
	s_mov_b32 s98, 0x8400000
	s_mov_b32 s99, 0
	v_lshl_add_u64 v[188:189], v[88:89], 0, s[98:99]
	global_load_dwordx4 v[184:187], v[188:189], off
	v_lshl_add_u64 v[188:189], v[94:95], 0, s[98:99]
	global_load_dwordx4 v[184:187], v[188:189], off
	v_lshl_add_u64 v[188:189], v[100:101], 0, s[98:99]
	global_load_dwordx4 v[184:187], v[188:189], off
	v_lshl_add_u64 v[188:189], v[106:107], 0, s[98:99]
	global_load_dwordx4 v[184:187], v[188:189], off
	s_branch .Lc3_pf_done
